# speedup vs baseline: 1.0021x; 1.0021x over previous
; __global__ void __launch_bounds__(512, 2) fwd_megakernel(Params p) {
amdhsa.kernels:
  - .agpr_count:     0
    .args:
      - .offset:         0
        .size:           160
        .value_kind:     by_value
      - .offset:         160
        .size:           4
        .value_kind:     hidden_block_count_x
      - .offset:         164
        .size:           4
        .value_kind:     hidden_block_count_y
      - .offset:         168
        .size:           4
        .value_kind:     hidden_block_count_z
      - .offset:         172
        .size:           2
        .value_kind:     hidden_group_size_x
      - .offset:         174
        .size:           2
        .value_kind:     hidden_group_size_y
      - .offset:         176
        .size:           2
        .value_kind:     hidden_group_size_z
      - .offset:         178
        .size:           2
        .value_kind:     hidden_remainder_x
      - .offset:         180
        .size:           2
        .value_kind:     hidden_remainder_y
      - .offset:         182
        .size:           2
        .value_kind:     hidden_remainder_z
      - .offset:         200
        .size:           8
        .value_kind:     hidden_global_offset_x
      - .offset:         208
        .size:           8
        .value_kind:     hidden_global_offset_y
      - .offset:         216
        .size:           8
        .value_kind:     hidden_global_offset_z
      - .offset:         224
        .size:           2
        .value_kind:     hidden_grid_dims
      - .offset:         248
        .size:           8
        .value_kind:     hidden_multigrid_sync_arg
      - .offset:         280
        .size:           4
        .value_kind:     hidden_dynamic_lds_size
    .group_segment_fixed_size: 0
    .kernarg_segment_align: 8
    .kernarg_segment_size: 416
    .language:       OpenCL C
    .language_version:
      - 2
      - 0
    .max_flat_workgroup_size: 512
    .name:           _Z14fwd_megakernel6Params
    .private_segment_fixed_size: 0
    .sgpr_count:     108
    .sgpr_spill_count: 241
    .symbol:         _Z14fwd_megakernel6Params.kd
    .uniform_work_group_size: 1
    .uses_dynamic_stack: false
    .vgpr_count:     256
    .vgpr_spill_count: 0
    .wavefront_size: 64
